# rows phase: the 8 bf16 mixer-output row loads per row were issued in 5 load/wait steps; now all 8 issued together (into v104-v119) right after the x-row loads, counted waits
# speedup vs baseline: 1.0180x; 1.0084x over previous
.LBB0_440:
	v_mad_i64_i32 v[68:69], s[0:1], v66, s70, v[62:63]
	global_load_dwordx2 v[104:105], v[68:69], off nt
	global_load_dwordx2 v[106:107], v[68:69], off offset:512 nt
	global_load_dwordx2 v[108:109], v[68:69], off offset:1024 nt
	global_load_dwordx2 v[110:111], v[68:69], off offset:1536 nt
	global_load_dwordx2 v[112:113], v[68:69], off offset:2048 nt
	global_load_dwordx2 v[114:115], v[68:69], off offset:2560 nt
	global_load_dwordx2 v[116:117], v[68:69], off offset:3072 nt
	global_load_dwordx2 v[118:119], v[68:69], off offset:3584 nt
	s_waitcnt vmcnt(7)
	v_mov_b64_e32 v[34:35], v[104:105]
	s_waitcnt vmcnt(6)
	v_mov_b64_e32 v[70:71], v[106:107]
	v_lshlrev_b32_e32 v144, 1, v38
	v_and_b32_e32 v33, 0xffff0000, v34
	v_and_b32_e32 v95, 0xffff0000, v70
	v_lshlrev_b32_e32 v32, 16, v34
	v_mul_f32_e32 v72, v33, v33
	v_lshlrev_b32_e32 v94, 16, v70
	v_mul_f32_e32 v70, v95, v95
	v_lshlrev_b32_e32 v34, 16, v35
	v_fmac_f32_e32 v72, v32, v32
	v_lshlrev_b32_e32 v92, 16, v71
	v_fmac_f32_e32 v70, v94, v94
	v_and_b32_e32 v35, 0xffff0000, v35
	v_fmac_f32_e32 v72, v34, v34
	v_and_b32_e32 v93, 0xffff0000, v71
	v_fmac_f32_e32 v70, v92, v92
	v_fmac_f32_e32 v72, v35, v35
	v_fmac_f32_e32 v70, v93, v93
	v_add_f32_e32 v72, v72, v70
	s_waitcnt vmcnt(5)
	v_mov_b64_e32 v[70:71], v[108:109]
	v_and_b32_e32 v91, 0xffff0000, v70
	v_lshlrev_b32_e32 v90, 16, v70
	v_mul_f32_e32 v70, v91, v91
	v_lshlrev_b32_e32 v88, 16, v71
	v_fmac_f32_e32 v70, v90, v90
	v_and_b32_e32 v89, 0xffff0000, v71
	v_fmac_f32_e32 v70, v88, v88
	v_fmac_f32_e32 v70, v89, v89
	v_add_f32_e32 v72, v72, v70
	s_waitcnt vmcnt(4)
	v_mov_b64_e32 v[70:71], v[110:111]
	v_and_b32_e32 v87, 0xffff0000, v70
	v_lshlrev_b32_e32 v86, 16, v70
	v_mul_f32_e32 v70, v87, v87
	v_lshlrev_b32_e32 v84, 16, v71
	v_fmac_f32_e32 v70, v86, v86
	v_and_b32_e32 v85, 0xffff0000, v71
	v_fmac_f32_e32 v70, v84, v84
	v_fmac_f32_e32 v70, v85, v85
	v_add_f32_e32 v74, v72, v70
	s_waitcnt vmcnt(3)
	v_mov_b64_e32 v[70:71], v[112:113]
	s_waitcnt vmcnt(2)
	v_mov_b64_e32 v[72:73], v[114:115]
	v_and_b32_e32 v82, 0xffff0000, v70
	v_lshlrev_b32_e32 v81, 16, v72
	v_and_b32_e32 v83, 0xffff0000, v72
	v_lshlrev_b32_e32 v79, 16, v73
	v_and_b32_e32 v77, 0xffff0000, v73
	s_waitcnt vmcnt(1)
	v_mov_b64_e32 v[96:97], v[116:117]
	s_waitcnt vmcnt(0)
	v_mov_b64_e32 v[72:73], v[118:119]
	v_lshlrev_b32_e32 v80, 16, v70
	v_lshlrev_b32_e32 v78, 16, v71
	v_and_b32_e32 v76, 0xffff0000, v71
	v_pk_mul_f32 v[70:71], v[82:83], v[82:83]
	v_and_b32_e32 v68, 0xffff0000, v96
	v_pk_fma_f32 v[70:71], v[80:81], v[80:81], v[70:71]
	v_and_b32_e32 v69, 0xffff0000, v72
	v_pk_fma_f32 v[70:71], v[78:79], v[78:79], v[70:71]
	v_lshlrev_b32_e32 v75, 16, v73
	v_pk_fma_f32 v[70:71], v[76:77], v[76:77], v[70:71]
	v_and_b32_e32 v73, 0xffff0000, v73
	v_add_f32_e32 v70, v74, v70
	v_add_f32_e32 v98, v70, v71
	v_lshlrev_b32_e32 v71, 16, v72
	v_lshlrev_b32_e32 v70, 16, v96
	v_lshlrev_b32_e32 v74, 16, v97
	v_and_b32_e32 v72, 0xffff0000, v97
	v_pk_mul_f32 v[96:97], v[68:69], v[68:69]
	s_nop 0
	v_pk_fma_f32 v[96:97], v[70:71], v[70:71], v[96:97]
	s_nop 0
	v_pk_fma_f32 v[96:97], v[74:75], v[74:75], v[96:97]
	s_nop 0
	v_pk_fma_f32 v[96:97], v[72:73], v[72:73], v[96:97]
	s_nop 0
	v_add_f32_e32 v96, v98, v96
	v_add_f32_e32 v96, v96, v97
	v_and_b32_e32 v97, 64, v181
	v_add_u32_e32 v97, 64, v97
	v_xor_b32_e32 v98, 32, v181
	v_cmp_lt_i32_e32 vcc, v98, v97
	s_nop 1
	v_cndmask_b32_e32 v98, v181, v98, vcc
	v_lshlrev_b32_e32 v98, 2, v98
	ds_bpermute_b32 v98, v98, v96
	s_waitcnt lgkmcnt(0)
	v_add_f32_e32 v96, v96, v98
	v_xor_b32_e32 v98, 16, v181
	v_cmp_lt_i32_e32 vcc, v98, v97
	s_nop 1
	v_cndmask_b32_e32 v98, v181, v98, vcc
	v_lshlrev_b32_e32 v98, 2, v98
	ds_bpermute_b32 v98, v98, v96
	s_waitcnt lgkmcnt(0)
	v_add_f32_e32 v96, v96, v98
	v_xor_b32_e32 v98, 8, v181
	v_cmp_lt_i32_e32 vcc, v98, v97
	s_nop 1
	v_cndmask_b32_e32 v98, v181, v98, vcc
	v_lshlrev_b32_e32 v98, 2, v98
	ds_bpermute_b32 v98, v98, v96
	s_waitcnt lgkmcnt(0)
	v_add_f32_e32 v96, v96, v98
	v_xor_b32_e32 v98, 4, v181
	v_cmp_lt_i32_e32 vcc, v98, v97
	s_nop 1
	v_cndmask_b32_e32 v98, v181, v98, vcc
	v_lshlrev_b32_e32 v98, 2, v98
	ds_bpermute_b32 v98, v98, v96
	s_waitcnt lgkmcnt(0)
	v_add_f32_e32 v96, v96, v98
	v_xor_b32_e32 v98, 2, v181
	v_cmp_lt_i32_e32 vcc, v98, v97
	s_nop 1
	v_cndmask_b32_e32 v98, v181, v98, vcc
	v_lshlrev_b32_e32 v98, 2, v98
	ds_bpermute_b32 v98, v98, v96
	s_waitcnt lgkmcnt(0)
	v_add_f32_e32 v96, v96, v98
	v_xor_b32_e32 v98, 1, v181
	v_cmp_lt_i32_e32 vcc, v98, v97
	s_nop 1
	v_cndmask_b32_e32 v97, v181, v98, vcc
	v_lshlrev_b32_e32 v97, 2, v97
	ds_bpermute_b32 v97, v97, v96
	ds_read_b128 v[98:101], v40
	s_waitcnt lgkmcnt(1)
	v_add_f32_e32 v96, v96, v97
	v_fmamk_f32 v96, v96, 0x3a000000, v176
	v_cmp_gt_f32_e32 vcc, s72, v96
	v_mul_f32_e32 v97, 0x4b800000, v96
	s_nop 0
	v_cndmask_b32_e32 v96, v96, v97, vcc
	v_rsq_f32_e32 v96, v96
	s_nop 0
	v_mul_f32_e32 v97, 0x45800000, v96
	v_cndmask_b32_e32 v96, v96, v97, vcc
	v_pk_mul_f32 v[32:33], v[32:33], v[96:97] op_sel_hi:[1,0]
	v_pk_mul_f32 v[34:35], v[34:35], v[96:97] op_sel_hi:[1,0]
	s_waitcnt lgkmcnt(0)
	v_pk_fma_f32 v[32:33], v[98:99], v[32:33], v[28:29]
	v_mov_b64_e32 v[28:29], s[2:3]
	v_pk_fma_f32 v[34:35], v[100:101], v[34:35], v[30:31]
	v_mad_i64_i32 v[98:99], s[0:1], v66, s70, v[28:29]
	s_mov_b64 s[0:1], -1
	s_and_b64 vcc, exec, s[36:37]
	v_mov_b32_e32 v31, v35
	v_mov_b32_e32 v30, v34
	v_mov_b32_e32 v29, v33
	v_mov_b32_e32 v28, v32
	s_cbranch_vccz .LBB0_442
	v_cvt_pk_bf16_f32 v30, v32, v33
	v_cvt_pk_bf16_f32 v31, v34, v35
	v_lshl_add_u64 v[28:29], v[98:99], 0, v[144:145]
	global_store_dwordx2 v[28:29], v[30:31], off
	v_lshlrev_b32_e32 v28, 16, v30
	v_and_b32_e32 v29, 0xffff0000, v30
	v_lshlrev_b32_e32 v30, 16, v31
	v_and_b32_e32 v31, 0xffff0000, v31
	s_mov_b64 s[0:1], 0
